# pipelined attention v9: all 32 exps speculative through the max chain, converts interleaved with the l-sum add chain
# baseline (speedup 1.0000x reference)
; DI float xor32_max(float x) { auto r = __builtin_amdgcn_permlane32_swap(__float_as_uint(x), __float_as_uint(x), false, false); return fmaxf(__uint_as_float(r[0]), __uint_as_float(r[1])); }
; DI float max3f(float a, float b, float c) { float r; asm("v_max3_f32 %0, %1, %2, %3" : "=v"(r) : "v"(a), "v"(b), "v"(c)); return r; }
; DI void attn_s(const unsigned char* sK, int tt, int qb, int qs, int sub, int l31, int h,
;                const bf16x8 (&qf)[4], f32x16 (&O)[4], float& m, float& l, bf16x8 (&pb)[4]) {
;     ...
;     float mx;
;     {
;         float t[11];
; #pragma unroll
;         for (int i = 0; i < 5; ++i) t[i] = max3f(st[0][3 * i], st[0][3 * i + 1], st[0][3 * i + 2]);
; #pragma unroll
;         for (int i = 0; i < 5; ++i) t[5 + i] = max3f(st[1][3 * i], st[1][3 * i + 1], st[1][3 * i + 2]);
;         t[10] = fmaxf(st[0][15], st[1][15]);
;         const float u0 = max3f(t[0], t[1], t[2]), u1 = max3f(t[3], t[4], t[5]), u2 = max3f(t[6], t[7], t[8]);
;         mx = max3f(max3f(u0, u1, u2), t[9], t[10]);
;     }
;     mx = xor32_max(mx);
;     if (tt == 0 || __builtin_amdgcn_ballot_w64(mx > 8.0f) != 0ull) {
;         const float delta = tt == 0 ? mx : fmaxf(mx, 0.f);
;         const float alpha = __builtin_amdgcn_exp2f(-delta);
;         m += delta;
;         l *= alpha;
; #pragma unroll
;         for (int d = 0; d < 4; ++d) O[d] = O[d] * alpha;
; #pragma unroll
;         for (int k2 = 0; k2 < 2; ++k2) st[k2] = st[k2] - delta;
;     }
; #pragma unroll
;     for (int k2 = 0; k2 < 2; ++k2)
; #pragma unroll
;         for (int i = 0; i < 16; ++i) st[k2][i] = __builtin_amdgcn_exp2f(st[k2][i]);
.Lpipe_nomask_l:
	v_max3_f32 v159, v82, v83, v84
	v_max3_f32 v160, v85, v86, v87
	v_max3_f32 v161, v88, v89, v90
	v_max3_f32 v162, v91, v92, v93
	v_max3_f32 v163, v94, v95, v96
	v_max3_f32 v164, v66, v67, v68
	v_max3_f32 v165, v69, v70, v71
	v_max3_f32 v166, v72, v73, v74
	v_max3_f32 v167, v75, v76, v77
	v_max3_f32 v168, v78, v79, v80
	v_max_f32_e32 v169, v81, v81
	v_max_f32_e32 v170, v97, v97
	v_exp_f32_e32 v82, v82
	v_exp_f32_e32 v83, v83
	v_max3_f32 v159, v159, v160, v161
	v_max3_f32 v160, v162, v163, v164
	v_exp_f32_e32 v84, v84
	v_exp_f32_e32 v85, v85
	v_max3_f32 v161, v165, v166, v167
	v_max_f32_e32 v169, v170, v169
	v_exp_f32_e32 v86, v86
	v_exp_f32_e32 v87, v87
	v_exp_f32_e32 v88, v88
	v_max3_f32 v159, v159, v160, v161
	v_exp_f32_e32 v89, v89
	v_exp_f32_e32 v90, v90
	v_exp_f32_e32 v91, v91
	s_mov_b32 s14, 0x41000000
	v_max3_f32 v159, v159, v168, v169
	v_exp_f32_e32 v92, v92
	v_exp_f32_e32 v93, v93
	v_exp_f32_e32 v94, v94
	v_mov_b32_e32 v160, v159
	v_exp_f32_e32 v95, v95
	v_exp_f32_e32 v96, v96
	v_exp_f32_e32 v97, v97
	v_permlane32_swap_b32_e32 v159, v160
	v_exp_f32_e32 v66, v66
	v_exp_f32_e32 v67, v67
	v_exp_f32_e32 v68, v68
	v_max_f32_e32 v160, v160, v160
	v_max_f32_e32 v159, v159, v159
	v_exp_f32_e32 v69, v69
	v_exp_f32_e32 v70, v70
	v_exp_f32_e32 v71, v71
	v_max_f32_e32 v159, v159, v160
	v_exp_f32_e32 v72, v72
	v_exp_f32_e32 v73, v73
	v_exp_f32_e32 v74, v74
	v_cmp_lt_f32_e32 vcc, s14, v159
	v_exp_f32_e32 v75, v75
	v_exp_f32_e32 v76, v76
	v_exp_f32_e32 v77, v77
	v_exp_f32_e32 v78, v78
	v_exp_f32_e32 v79, v79
	v_exp_f32_e32 v80, v80
	v_exp_f32_e32 v81, v81
	s_cbranch_vccz .Lpipe_norescale_l
	v_max_f32_e32 v159, v159, v159
	v_max_f32_e32 v159, 0, v159
	v_exp_f32_e64 v160, -v159
	v_add_f32_e32 v157, v157, v159
	v_xor_b32_e32 v240, 0x80000000, v157
	v_mov_b32_e32 v241, v240
	v_mov_b32_e32 v242, v240
	v_mov_b32_e32 v243, v240
	v_mov_b32_e32 v244, v240
	v_mov_b32_e32 v245, v240
	v_mov_b32_e32 v246, v240
	v_mov_b32_e32 v247, v240
	v_mov_b32_e32 v248, v240
	v_mov_b32_e32 v249, v240
	v_mov_b32_e32 v250, v240
	v_mov_b32_e32 v251, v240
	v_mov_b32_e32 v252, v240
	v_mov_b32_e32 v253, v240
	v_mov_b32_e32 v254, v240
	v_mov_b32_e32 v255, v240
	v_mul_f32_e32 v1, v1, v160
	v_pk_mul_f32 v[64:65], v[64:65], v[160:161] op_sel_hi:[1,0]
	v_pk_mul_f32 v[62:63], v[62:63], v[160:161] op_sel_hi:[1,0]
	v_pk_mul_f32 v[60:61], v[60:61], v[160:161] op_sel_hi:[1,0]
	v_pk_mul_f32 v[58:59], v[58:59], v[160:161] op_sel_hi:[1,0]
	v_pk_mul_f32 v[56:57], v[56:57], v[160:161] op_sel_hi:[1,0]
	v_pk_mul_f32 v[54:55], v[54:55], v[160:161] op_sel_hi:[1,0]
	v_pk_mul_f32 v[52:53], v[52:53], v[160:161] op_sel_hi:[1,0]
	v_pk_mul_f32 v[50:51], v[50:51], v[160:161] op_sel_hi:[1,0]
	v_pk_mul_f32 v[48:49], v[48:49], v[160:161] op_sel_hi:[1,0]
	v_pk_mul_f32 v[46:47], v[46:47], v[160:161] op_sel_hi:[1,0]
	v_pk_mul_f32 v[44:45], v[44:45], v[160:161] op_sel_hi:[1,0]
	v_pk_mul_f32 v[42:43], v[42:43], v[160:161] op_sel_hi:[1,0]
	v_pk_mul_f32 v[40:41], v[40:41], v[160:161] op_sel_hi:[1,0]
	v_pk_mul_f32 v[38:39], v[38:39], v[160:161] op_sel_hi:[1,0]
	v_pk_mul_f32 v[36:37], v[36:37], v[160:161] op_sel_hi:[1,0]
	v_pk_mul_f32 v[34:35], v[34:35], v[160:161] op_sel_hi:[1,0]
	v_pk_mul_f32 v[32:33], v[32:33], v[160:161] op_sel_hi:[1,0]
	v_pk_mul_f32 v[30:31], v[30:31], v[160:161] op_sel_hi:[1,0]
	v_pk_mul_f32 v[28:29], v[28:29], v[160:161] op_sel_hi:[1,0]
	v_pk_mul_f32 v[26:27], v[26:27], v[160:161] op_sel_hi:[1,0]
	v_pk_mul_f32 v[24:25], v[24:25], v[160:161] op_sel_hi:[1,0]
	v_pk_mul_f32 v[22:23], v[22:23], v[160:161] op_sel_hi:[1,0]
	v_pk_mul_f32 v[20:21], v[20:21], v[160:161] op_sel_hi:[1,0]
	v_pk_mul_f32 v[18:19], v[18:19], v[160:161] op_sel_hi:[1,0]
	v_pk_mul_f32 v[16:17], v[16:17], v[160:161] op_sel_hi:[1,0]
	v_pk_mul_f32 v[14:15], v[14:15], v[160:161] op_sel_hi:[1,0]
	v_pk_mul_f32 v[12:13], v[12:13], v[160:161] op_sel_hi:[1,0]
	v_pk_mul_f32 v[10:11], v[10:11], v[160:161] op_sel_hi:[1,0]
	v_pk_mul_f32 v[8:9], v[8:9], v[160:161] op_sel_hi:[1,0]
	v_pk_mul_f32 v[6:7], v[6:7], v[160:161] op_sel_hi:[1,0]
	v_pk_mul_f32 v[4:5], v[4:5], v[160:161] op_sel_hi:[1,0]
	v_pk_mul_f32 v[2:3], v[2:3], v[160:161] op_sel_hi:[1,0]
	v_mul_f32_e32 v66, v66, v160
	v_mul_f32_e32 v67, v67, v160
	v_mul_f32_e32 v68, v68, v160
	v_mul_f32_e32 v69, v69, v160
	v_mul_f32_e32 v70, v70, v160
	v_mul_f32_e32 v71, v71, v160
	v_mul_f32_e32 v72, v72, v160
	v_mul_f32_e32 v73, v73, v160
	v_mul_f32_e32 v74, v74, v160
	v_mul_f32_e32 v75, v75, v160
	v_mul_f32_e32 v76, v76, v160
	v_mul_f32_e32 v77, v77, v160
	v_mul_f32_e32 v78, v78, v160
	v_mul_f32_e32 v79, v79, v160
	v_mul_f32_e32 v80, v80, v160
	v_mul_f32_e32 v81, v81, v160
	v_mul_f32_e32 v82, v82, v160
	v_mul_f32_e32 v83, v83, v160
	v_mul_f32_e32 v84, v84, v160
	v_mul_f32_e32 v85, v85, v160
	v_mul_f32_e32 v86, v86, v160
	v_mul_f32_e32 v87, v87, v160
	v_mul_f32_e32 v88, v88, v160
	v_mul_f32_e32 v89, v89, v160
	v_mul_f32_e32 v90, v90, v160
	v_mul_f32_e32 v91, v91, v160
	v_mul_f32_e32 v92, v92, v160
	v_mul_f32_e32 v93, v93, v160
	v_mul_f32_e32 v94, v94, v160
	v_mul_f32_e32 v95, v95, v160
	v_mul_f32_e32 v96, v96, v160
	v_mul_f32_e32 v97, v97, v160
; #define MFMA32(a, b, c) __builtin_amdgcn_mfma_f32_32x32x16_bf16((a), (b), (c), 0, 0, 0)
; DI unsigned pk2(float a, float b) { f32x2 v = {a, b}; return __builtin_bit_cast(unsigned, __builtin_convertvector(v, bfv2)); }
; DI void attn_s(const unsigned char* sK, int tt, int qb, int qs, int sub, int l31, int h,
;                const bf16x8 (&qf)[4], f32x16 (&O)[4], float& m, float& l, bf16x8 (&pb)[4]) {
;     ...
; #pragma unroll
;     for (int k2 = 0; k2 < 2; ++k2)
; #pragma unroll
;         for (int i = 0; i < 16; ++i) st[k2][i] = __builtin_amdgcn_exp2f(st[k2][i]);
;     {
;         const f32x16 sv = st[0] + st[1];
;         const float ps = (((sv[0] + sv[1]) + (sv[2] + sv[3])) + ((sv[4] + sv[5]) + (sv[6] + sv[7]))) + (((sv[8] + sv[9]) + (sv[10] + sv[11])) + ((sv[12] + sv[13]) + (sv[14] + sv[15])));
;         l += ps;
;     }
; #pragma unroll
;     for (int k4 = 0; k4 < 4; ++k4) {
;         const int k2 = k4 >> 1, o8 = 8 * (k4 & 1);
;         u32x4 pk;
;         pk.x = pk2(st[k2][o8 + 0], st[k2][o8 + 1]); pk.y = pk2(st[k2][o8 + 2], st[k2][o8 + 3]);
;         pk.z = pk2(st[k2][o8 + 4], st[k2][o8 + 5]); pk.w = pk2(st[k2][o8 + 6], st[k2][o8 + 7]);
;         pb[k4] = __builtin_bit_cast(bf16x8, pk);
;     }
; DI void attn_pv(const unsigned char* sV, int l31, int h, const bf16x8 (&pb)[4], f32x16 (&O)[4]) {
;     ...
;         for (int d = 0; d < 4; ++d) O[d] = MFMA32(va[d], pb[0], O[d]);
;         __builtin_amdgcn_sched_barrier(0);
; #pragma unroll
;         for (int d = 0; d < 4; ++d) va[d] = *(const bf16x8*)(vb + d * 32 * A_VROWB + 64);
;         __builtin_amdgcn_sched_barrier(0);
; #pragma unroll
;         for (int d = 0; d < 4; ++d) O[d] = MFMA32(vc[d], pb[1], O[d]);
;         __builtin_amdgcn_sched_barrier(0);
; #pragma unroll
;         for (int d = 0; d < 4; ++d) vc[d] = *(const bf16x8*)(vb + d * 32 * A_VROWB + 96);
;         __builtin_amdgcn_sched_barrier(0);
; #pragma unroll
;         for (int d = 0; d < 4; ++d) O[d] = MFMA32(va[d], pb[2], O[d]);
;         __builtin_amdgcn_sched_barrier(0);
; #pragma unroll
;         for (int d = 0; d < 4; ++d) O[d] = MFMA32(vc[d], pb[3], O[d]);
.Lpipe_norescale_l:
	v_cvt_pk_bf16_f32 v224, v66, v67
	v_cvt_pk_bf16_f32 v225, v68, v69
	v_cvt_pk_bf16_f32 v226, v70, v71
	v_cvt_pk_bf16_f32 v227, v72, v73
	v_cvt_pk_bf16_f32 v228, v74, v75
	v_cvt_pk_bf16_f32 v229, v76, v77
	v_cvt_pk_bf16_f32 v230, v78, v79
	v_cvt_pk_bf16_f32 v231, v80, v81
	v_pk_add_f32 v[68:69], v[84:85], v[68:69]
	v_pk_add_f32 v[66:67], v[82:83], v[66:67]
	v_pk_add_f32 v[72:73], v[88:89], v[72:73]
	v_cvt_pk_bf16_f32 v216, v82, v83
	v_pk_add_f32 v[70:71], v[86:87], v[70:71]
	v_add_f32_e32 v66, v66, v67
	v_add_f32_e32 v67, v68, v69
	v_cvt_pk_bf16_f32 v217, v84, v85
	v_add_f32_e32 v66, v66, v67
	v_add_f32_e32 v67, v70, v71
	v_add_f32_e32 v68, v72, v73
	v_cvt_pk_bf16_f32 v218, v86, v87
	v_pk_add_f32 v[76:77], v[92:93], v[76:77]
	v_pk_add_f32 v[74:75], v[90:91], v[74:75]
	v_add_f32_e32 v67, v67, v68
	v_cvt_pk_bf16_f32 v219, v88, v89
	v_pk_add_f32 v[80:81], v[96:97], v[80:81]
	v_pk_add_f32 v[78:79], v[94:95], v[78:79]
	v_add_f32_e32 v66, v66, v67
	v_cvt_pk_bf16_f32 v220, v90, v91
	v_add_f32_e32 v67, v74, v75
	v_add_f32_e32 v68, v76, v77
	v_add_f32_e32 v67, v67, v68
	v_cvt_pk_bf16_f32 v221, v92, v93
	v_add_f32_e32 v68, v78, v79
	v_add_f32_e32 v69, v80, v81
	v_add_f32_e32 v68, v68, v69
	v_cvt_pk_bf16_f32 v222, v94, v95
	v_add_f32_e32 v67, v67, v68
	v_add_f32_e32 v66, v66, v67
	v_add_f32_e32 v1, v1, v66
	v_cvt_pk_bf16_f32 v223, v96, v97
	v_add_u32_e32 v158, 64, v158
	s_mov_b32 s13, s7
	s_add_i32 s4, s7, 1
	s_cmp_lg_u32 s7, 2
	s_cselect_b32 s7, s4, 0
	s_add_i32 s12, s12, 1
	s_cmp_eq_u32 s11, s12
	s_cbranch_scc1 .Lpipe_final
	s_barrier
	s_setprio 1
	s_mul_i32 s98, s13, 0x8c00
	v_add3_u32 v185, s98, v155, v154
	ds_read_b128 v[160:163], v185
	ds_read_b128 v[164:167], v185 offset:32
	ds_read_b128 v[168:171], v185 offset:8704
	ds_read_b128 v[196:199], v185 offset:8736
	s_waitcnt lgkmcnt(11)
	v_mfma_f32_32x32x16_bf16 v[50:65], v[172:175], v[216:219], v[50:65]
	s_waitcnt lgkmcnt(10)
	v_mfma_f32_32x32x16_bf16 v[34:49], v[176:179], v[216:219], v[34:49]
	s_waitcnt lgkmcnt(9)
	v_mfma_f32_32x32x16_bf16 v[18:33], v[180:183], v[216:219], v[18:33]
	s_waitcnt lgkmcnt(8)
	v_mfma_f32_32x32x16_bf16 v[2:17], v[192:195], v[216:219], v[2:17]
	ds_read_b128 v[172:175], v185 offset:64
	ds_read_b128 v[176:179], v185 offset:96
	ds_read_b128 v[180:183], v185 offset:8768
	ds_read_b128 v[192:195], v185 offset:8800
	s_waitcnt lgkmcnt(11)
	v_mfma_f32_32x32x16_bf16 v[50:65], v[200:203], v[220:223], v[50:65]
	s_waitcnt lgkmcnt(10)
	v_mfma_f32_32x32x16_bf16 v[34:49], v[204:207], v[220:223], v[34:49]
	s_waitcnt lgkmcnt(9)
	v_mfma_f32_32x32x16_bf16 v[18:33], v[208:211], v[220:223], v[18:33]
	s_waitcnt lgkmcnt(8)
	v_mfma_f32_32x32x16_bf16 v[2:17], v[212:215], v[220:223], v[2:17]
	ds_read_b128 v[200:203], v191 offset:17472
	ds_read_b128 v[204:207], v191 offset:22080
	ds_read_b128 v[208:211], v191 offset:26688
	ds_read_b128 v[212:215], v191 offset:31296
	s_waitcnt lgkmcnt(11)
	v_mfma_f32_32x32x16_bf16 v[82:97], v[160:163], v[100:103], v[240:255]
	s_waitcnt lgkmcnt(9)
	v_mfma_f32_32x32x16_bf16 v[66:81], v[168:171], v[100:103], v[240:255]
	v_mfma_f32_32x32x16_bf16 v[82:97], v[164:167], v[104:107], v[82:97]
	s_waitcnt lgkmcnt(8)
	v_mfma_f32_32x32x16_bf16 v[66:81], v[196:199], v[104:107], v[66:81]
	ds_read_b128 v[160:163], v191 offset:17504
	ds_read_b128 v[164:167], v191 offset:22112
	ds_read_b128 v[168:171], v191 offset:26720
	ds_read_b128 v[196:199], v191 offset:31328
	s_waitcnt lgkmcnt(11)
	v_mfma_f32_32x32x16_bf16 v[82:97], v[172:175], v[108:111], v[82:97]
	s_waitcnt lgkmcnt(9)
	v_mfma_f32_32x32x16_bf16 v[66:81], v[180:183], v[108:111], v[66:81]
	v_mfma_f32_32x32x16_bf16 v[82:97], v[176:179], v[112:115], v[82:97]
	s_waitcnt lgkmcnt(8)
	v_mfma_f32_32x32x16_bf16 v[66:81], v[192:195], v[112:115], v[66:81]
	s_add_i32 s14, s12, 0x42
	s_cmp_ge_i32 s14, s6
	s_cbranch_scc1 .Lpipe_nost_l
	s_mul_i32 s4, s7, 0x8c00
	s_add_i32 s4, s4, 0
	v_add_u32_e32 v184, s4, v140
	v_add_u32_e32 v185, v184, v139
	v_add_u32_e32 v184, v184, v141
	s_waitcnt vmcnt(3)
	ds_write_b128 v185, v[116:119]
	s_waitcnt vmcnt(2)
	ds_write_b128 v184, v[120:123]
	v_add3_u32 v184, s4, v150, v151
	v_add_u32_e32 v185, v184, v152
	v_add_u32_e32 v184, v184, v153
	v_add_u32_e32 v185, 0x4000, v185
	v_add_u32_e32 v184, 0x4000, v184
	s_waitcnt vmcnt(1)
	ds_write2_b64 v185, v[124:125], v[126:127] offset0:128 offset1:130
	s_waitcnt vmcnt(0)
	ds_write2_b64 v184, v[128:129], v[130:131] offset0:128 offset1:130
